# NSA compressed branch pass 1: masked scores set to -inf in place (exp2 gives exact zeros), second select per score and masked copies removed
# speedup vs baseline: 1.0064x; 1.0064x over previous
.Lnsa_c1_nopf:
	s_waitcnt lgkmcnt(0)
	s_barrier
	ds_read_b128 v[2:5], v63
	ds_read_b128 v[28:31], v63 offset:32
	ds_read_b128 v[220:223], v63 offset:64
	ds_read_b128 v[224:227], v63 offset:96
	s_waitcnt lgkmcnt(3)
	v_mfma_f32_32x32x16_bf16 v[2:17], v[2:5], v[96:99], 0
	s_waitcnt lgkmcnt(2)
	v_mfma_f32_32x32x16_bf16 v[2:17], v[28:31], v[100:103], v[2:17]
	s_waitcnt lgkmcnt(1)
	v_mfma_f32_32x32x16_bf16 v[2:17], v[220:223], v[104:107], v[2:17]
	s_waitcnt lgkmcnt(0)
	v_mfma_f32_32x32x16_bf16 v[2:17], v[224:227], v[108:111], v[2:17]
	s_nop 10
	v_mov_b32_e32 v28, 0xff800000
	v_cndmask_b32_e64 v2, v2, v28, s[38:39]
	v_cndmask_b32_e64 v3, v3, v28, s[40:41]
	v_cndmask_b32_e64 v4, v4, v28, s[42:43]
	v_cndmask_b32_e64 v5, v5, v28, s[44:45]
	v_cndmask_b32_e64 v6, v6, v28, s[46:47]
	v_cndmask_b32_e64 v7, v7, v28, s[48:49]
	v_cndmask_b32_e64 v8, v8, v28, s[50:51]
	v_cndmask_b32_e64 v9, v9, v28, s[52:53]
	v_cndmask_b32_e64 v10, v10, v28, s[54:55]
	v_cndmask_b32_e64 v11, v11, v28, s[56:57]
	v_cndmask_b32_e64 v12, v12, v28, s[58:59]
	v_cndmask_b32_e64 v13, v13, v28, s[60:61]
	v_cndmask_b32_e64 v14, v14, v28, s[62:63]
	v_cndmask_b32_e64 v15, v15, v28, s[64:65]
	v_cndmask_b32_e64 v16, v16, v28, s[66:67]
	v_cndmask_b32_e32 v17, v17, v28, vcc
	v_max3_f32 v19, v2, v3, v4
	v_max3_f32 v29, v5, v6, v7
	v_max3_f32 v19, v19, v8, v9
	v_max3_f32 v29, v29, v10, v11
	v_max3_f32 v19, v19, v12, v13
	v_max3_f32 v29, v29, v14, v15
	v_max3_f32 v19, v19, v16, v17
	v_max3_f32 v19, v27, v19, v29
	v_sub_f32_e32 v2, v2, v19
	v_sub_f32_e32 v3, v3, v19
	v_exp_f32_e32 v2, v2
	v_sub_f32_e32 v4, v4, v19
	v_exp_f32_e32 v3, v3
	v_sub_f32_e32 v5, v5, v19
	v_exp_f32_e32 v4, v4
	v_add_f32_e32 v2, v3, v2
	v_sub_f32_e32 v6, v6, v19
	v_exp_f32_e32 v5, v5
	v_add_f32_e32 v2, v4, v2
	v_sub_f32_e32 v7, v7, v19
	v_exp_f32_e32 v6, v6
	v_add_f32_e32 v2, v5, v2
	v_sub_f32_e32 v8, v8, v19
	v_exp_f32_e32 v7, v7
	v_add_f32_e32 v2, v6, v2
	v_sub_f32_e32 v9, v9, v19
	v_exp_f32_e32 v8, v8
	v_add_f32_e32 v2, v7, v2
	v_sub_f32_e32 v10, v10, v19
	v_exp_f32_e32 v9, v9
	v_add_f32_e32 v2, v8, v2
	v_sub_f32_e32 v11, v11, v19
	v_exp_f32_e32 v10, v10
	v_add_f32_e32 v2, v9, v2
	v_sub_f32_e32 v12, v12, v19
	v_exp_f32_e32 v11, v11
	v_add_f32_e32 v2, v10, v2
	v_sub_f32_e32 v13, v13, v19
	v_exp_f32_e32 v12, v12
	v_add_f32_e32 v2, v11, v2
	v_sub_f32_e32 v14, v14, v19
	v_exp_f32_e32 v13, v13
	v_add_f32_e32 v2, v12, v2
	v_sub_f32_e32 v15, v15, v19
	v_exp_f32_e32 v14, v14
	v_add_f32_e32 v2, v13, v2
	v_sub_f32_e32 v16, v16, v19
	v_exp_f32_e32 v15, v15
	v_add_f32_e32 v2, v14, v2
	v_sub_f32_e32 v17, v17, v19
	v_exp_f32_e32 v16, v16
	v_add_f32_e32 v2, v15, v2
	v_sub_f32_e32 v27, v27, v19
	v_exp_f32_e32 v17, v17
	v_add_f32_e32 v2, v16, v2
	v_exp_f32_e32 v27, v27
	v_add_f32_e32 v6, v17, v2
	v_fmac_f32_e32 v6, v32, v27
	s_cbranch_scc0 .LBB0_184
	v_readlane_b32 s64, v253, 17
	v_readlane_b32 s65, v253, 18
	s_mov_b64 s[66:67], s[14:15]
	s_branch .LBB0_187
